# Wgu GEMM epilogue: counted wait, vmcnt(4) before the rss-to-rstd conversion and vmcnt(0) only before the first bias use (on top of v18)
# speedup vs baseline: 1.0079x; 1.0079x over previous
; __device__ __forceinline__ float rstd_of(const rss_t* rss, size_t row) { return __builtin_amdgcn_rsqf((float)rss[row] * (1.0f / (1048576.0f * 1024.0f)) + 1e-6f); }
;     __device__ __forceinline__ void operator()(const f32x4 (&acc)[2][2][4][2], const Unit& u, int wr, int wc, int fr, int fq) const {
;         const int b = batch_of_tile(u.pm), col0 = u.pn * HALF + wc * 32 + 8 * fq;
;         const float* bp = bias + (size_t)b * 5632 + u.pn * BM + wc * 32 + 8 * fq;
;         const f32x4 bg0 = *(const f32x4*)bp, bg1 = *(const f32x4*)(bp + 4), bu0 = *(const f32x4*)(bp + HALF), bu1 = *(const f32x4*)(bp + HALF + 4);
;         float rsv[2][4];
; #pragma unroll
;         for (int ai = 0; ai < 2; ++ai)
; #pragma unroll
;             for (int m = 0; m < 4; ++m) rsv[ai][m] = rstd_of(rss, (size_t)(u.pm * BM + ai * HALF + wr * 64 + m * 16 + fr));
.LBB0_698:
	v_lshl_add_u32 v180, s52, 8, v161
	v_ashrrev_i32_e32 v181, 31, v180
	v_or_b32_e32 v178, 16, v180
	v_or_b32_e32 v174, 32, v180
	v_or_b32_e32 v170, 48, v180
	v_lshl_add_u64 v[128:129], v[180:181], 3, s[40:41]
	v_ashrrev_i32_e32 v179, 31, v178
	v_ashrrev_i32_e32 v175, 31, v174
	v_ashrrev_i32_e32 v171, 31, v170
	v_lshl_add_u64 v[130:131], v[178:179], 3, s[40:41]
	v_lshl_add_u64 v[132:133], v[174:175], 3, s[40:41]
	v_lshl_add_u64 v[134:135], v[170:171], 3, s[40:41]
	global_load_dwordx2 v[176:177], v[128:129], off
	global_load_dwordx2 v[182:183], v[130:131], off
	global_load_dwordx2 v[184:185], v[132:133], off
	global_load_dwordx2 v[186:187], v[134:135], off
	v_add_u32_e32 v166, 0x80, v180
	v_ashrrev_i32_e32 v167, 31, v166
	v_lshl_add_u64 v[128:129], v[166:167], 3, s[40:41]
	global_load_dwordx2 v[188:189], v[128:129], off
	v_add_u32_e32 v162, 0x90, v180
	v_ashrrev_i32_e32 v163, 31, v162
	v_lshl_add_u64 v[128:129], v[162:163], 3, s[40:41]
	global_load_dwordx2 v[190:191], v[128:129], off
	s_sub_i32 s45, s52, 64
	s_lshr_b32 s45, s45, 5
	v_add_u32_e32 v158, 0xa0, v180
	s_add_i32 s45, s45, 1
	v_ashrrev_i32_e32 v159, 31, v158
	v_lshl_add_u64 v[128:129], v[158:159], 3, s[40:41]
	s_cmp_gt_i32 s52, 63
	global_load_dwordx2 v[194:195], v[128:129], off
	s_cselect_b32 s45, s45, 0
	s_mul_hi_u32 s47, s45, 0x5800
	s_mulk_i32 s45, 0x5800
	s_add_u32 s45, s67, s45
	v_add_u32_e32 v156, 0xb0, v180
	s_addc_u32 s47, s68, s47
	s_lshl_b32 s54, s82, 8
	v_ashrrev_i32_e32 v157, 31, v156
	s_ashr_i32 s55, s54, 31
	v_lshl_add_u64 v[128:129], v[156:157], 3, s[40:41]
	s_lshl_b64 s[54:55], s[54:55], 2
	global_load_dwordx2 v[196:197], v[128:129], off
	s_add_u32 s45, s45, s54
	s_addc_u32 s47, s47, s55
	s_add_u32 s54, s45, s81
	s_addc_u32 s55, s47, 0
	v_lshl_add_u64 v[136:137], v[150:151], 2, s[54:55]
	global_load_dwordx4 v[132:135], v[136:137], off offset:16
	global_load_dwordx4 v[140:143], v[136:137], off
	global_load_dwordx4 v[128:131], v[136:137], off offset:528
	s_nop 0
	global_load_dwordx4 v[136:139], v[136:137], off offset:512
	s_andn2_b64 vcc, exec, s[36:37]
	s_mov_b64 s[36:37], -1
	s_mov_b64 s[84:85], s[12:13]
	s_waitcnt vmcnt(4)
	v_ffbh_u32_e32 v157, v177
	v_min_u32_e32 v157, 32, v157
	v_ffbh_u32_e32 v159, v183
	v_lshlrev_b64 v[176:177], v157, v[176:177]
	v_min_u32_e32 v159, 32, v159
	v_ffbh_u32_e32 v160, v185
	v_min_u32_e32 v167, 1, v176
	v_lshlrev_b64 v[182:183], v159, v[182:183]
	v_ffbh_u32_e32 v163, v187
	v_min_u32_e32 v160, 32, v160
	v_or_b32_e32 v167, v177, v167
	v_min_u32_e32 v168, 1, v182
	v_min_u32_e32 v163, 32, v163
	v_lshlrev_b64 v[184:185], v160, v[184:185]
	v_cvt_f32_u32_e32 v167, v167
	v_or_b32_e32 v168, v183, v168
	v_lshlrev_b64 v[186:187], v163, v[186:187]
	v_min_u32_e32 v171, 1, v184
	v_cvt_f32_u32_e32 v168, v168
	v_ffbh_u32_e32 v164, v189
	v_min_u32_e32 v172, 1, v186
	v_or_b32_e32 v171, v185, v171
	v_sub_u32_e32 v157, 32, v157
	v_min_u32_e32 v164, 32, v164
	v_or_b32_e32 v172, v187, v172
	v_cvt_f32_u32_e32 v171, v171
	v_sub_u32_e32 v159, 32, v159
	v_lshlrev_b64 v[188:189], v164, v[188:189]
	v_cvt_f32_u32_e32 v172, v172
	v_ldexp_f32 v157, v167, v157
	v_min_u32_e32 v175, 1, v188
	v_fmamk_f32 v157, v157, 0x30800000, v220
	v_ldexp_f32 v159, v168, v159
	v_sub_u32_e32 v160, 32, v160
	v_or_b32_e32 v175, v189, v175
	v_rsq_f32_e32 v184, v157
	v_fmamk_f32 v157, v159, 0x30800000, v220
	v_sub_u32_e32 v163, 32, v163
	v_ldexp_f32 v160, v171, v160
	v_rsq_f32_e32 v186, v157
	v_cvt_f32_u32_e32 v157, v175
	v_ldexp_f32 v163, v172, v163
	v_fmamk_f32 v159, v160, 0x30800000, v220
	v_rsq_f32_e32 v182, v159
	v_fmamk_f32 v159, v163, 0x30800000, v220
	v_rsq_f32_e32 v176, v159
	v_sub_u32_e32 v159, 32, v164
	v_ldexp_f32 v157, v157, v159
	v_ffbh_u32_e32 v159, v191
	v_min_u32_e32 v159, 32, v159
	v_lshlrev_b64 v[188:189], v159, v[190:191]
	v_min_u32_e32 v160, 1, v188
	v_or_b32_e32 v160, v189, v160
	v_cvt_f32_u32_e32 v160, v160
	v_fmamk_f32 v157, v157, 0x30800000, v220
	v_rsq_f32_e32 v172, v157
	v_sub_u32_e32 v157, 32, v159
	v_ffbh_u32_e32 v159, v195
	v_min_u32_e32 v159, 32, v159
	v_lshlrev_b64 v[188:189], v159, v[194:195]
	v_ldexp_f32 v157, v160, v157
	v_min_u32_e32 v160, 1, v188
	v_or_b32_e32 v160, v189, v160
	v_cvt_f32_u32_e32 v160, v160
	v_fmamk_f32 v157, v157, 0x30800000, v220
	v_rsq_f32_e32 v168, v157
	v_sub_u32_e32 v157, 32, v159
	v_ffbh_u32_e32 v159, v197
	v_min_u32_e32 v159, 32, v159
	v_lshlrev_b64 v[188:189], v159, v[196:197]
	v_ldexp_f32 v157, v160, v157
	v_min_u32_e32 v160, 1, v188
	s_waitcnt vmcnt(0)
; __device__ __forceinline__ unsigned cvt_pk_bf16(float lo, float hi) { unsigned r; asm volatile("v_cvt_pk_bf16_f32 %0, %1, %2" : "=v"(r) : "v"(lo), "v"(hi)); return r; }
;     __device__ __forceinline__ void operator()(const f32x4 (&acc)[2][2][4][2], const Unit& u, int wr, int wc, int fr, int fq) const {
;     ...
; #pragma unroll
;         for (int ai = 0; ai < 2; ++ai)
; #pragma unroll
;             for (int m = 0; m < 4; ++m) { const size_t row = (size_t)(u.pm * BM + ai * HALF + wr * 64 + m * 16 + fr); const float rs = rsv[ai][m];
;                 u32x4 w;
; #pragma unroll
;                 for (int n = 0; n < 2; ++n)
; #pragma unroll
;                     for (int h = 0; h < 2; ++h) {
;                         const f32x2_t ag = {acc[ai][0][m][n][2 * h], acc[ai][0][m][n][2 * h + 1]}, au = {acc[ai][1][m][n][2 * h], acc[ai][1][m][n][2 * h + 1]};
;                         const f32x4 bgv = n ? bg1 : bg0, buv = n ? bu1 : bu0;
;                         const f32x2_t bg = {bgv[2 * h], bgv[2 * h + 1]}, bu = {buv[2 * h], buv[2 * h + 1]};
;                         const f32x2_t g = ag * rs + bg, up = au * rs + bu, ea = g * (-1.4426950408889634f);
;                         f32x2_t ex; ex.x = __builtin_amdgcn_exp2f(ea.x); ex.y = __builtin_amdgcn_exp2f(ea.y);
;                         const f32x2_t d = ex + 1.0f; f32x2_t rc; rc.x = __builtin_amdgcn_rcpf(d.x); rc.y = __builtin_amdgcn_rcpf(d.y);
;                         const f32x2_t o = (g * up) * rc;
;                         w[n * 2 + h] = cvt_pk_bf16(o.x, o.y); }
;                 __builtin_nontemporal_store(w, (u32x4*)(act + row * XDFF + col0)); }
	v_pk_fma_f32 v[124:125], v[124:125], v[184:185], v[140:141] op_sel_hi:[1,0,1]
	v_or_b32_e32 v160, v189, v160
	v_pk_mul_f32 v[188:189], v[124:125], s[28:29] op_sel_hi:[1,0]
	v_pk_fma_f32 v[120:121], v[120:121], v[184:185], v[136:137] op_sel_hi:[1,0,1]
	v_exp_f32_e32 v188, v188
	v_exp_f32_e32 v189, v189
	v_pk_mul_f32 v[120:121], v[124:125], v[120:121]
	v_pk_fma_f32 v[124:125], v[126:127], v[184:185], v[142:143] op_sel_hi:[1,0,1]
	v_pk_fma_f32 v[116:117], v[116:117], v[184:185], v[132:133] op_sel_hi:[1,0,1]
	v_pk_mul_f32 v[126:127], v[124:125], s[28:29] op_sel_hi:[1,0]
	v_pk_add_f32 v[188:189], v[188:189], 1.0 op_sel_hi:[1,0]
	v_exp_f32_e32 v126, v126
	v_exp_f32_e32 v127, v127
	v_rcp_f32_e32 v188, v188
	v_rcp_f32_e32 v189, v189
	v_pk_fma_f32 v[122:123], v[122:123], v[184:185], v[138:139] op_sel_hi:[1,0,1]
	v_pk_add_f32 v[126:127], v[126:127], 1.0 op_sel_hi:[1,0]
	v_pk_fma_f32 v[118:119], v[118:119], v[184:185], v[134:135] op_sel_hi:[1,0,1]
	v_pk_mul_f32 v[120:121], v[120:121], v[188:189]
	v_rcp_f32_e32 v126, v126
	v_rcp_f32_e32 v127, v127
	v_pk_mul_f32 v[188:189], v[116:117], s[28:29] op_sel_hi:[1,0]
	v_pk_mul_f32 v[122:123], v[124:125], v[122:123]
	v_exp_f32_e32 v188, v188
	v_exp_f32_e32 v189, v189
	v_pk_mul_f32 v[124:125], v[118:119], s[28:29] op_sel_hi:[1,0]
	v_pk_mul_f32 v[122:123], v[122:123], v[126:127]
	v_exp_f32_e32 v124, v124
	v_exp_f32_e32 v125, v125
	v_cvt_pk_bf16_f32 v120, v120, v121
	v_cvt_pk_bf16_f32 v121, v122, v123
	v_pk_add_f32 v[122:123], v[188:189], 1.0 op_sel_hi:[1,0]
	v_pk_fma_f32 v[112:113], v[112:113], v[184:185], v[128:129] op_sel_hi:[1,0,1]
	v_rcp_f32_e32 v122, v122
	v_rcp_f32_e32 v123, v123
	v_pk_mul_f32 v[112:113], v[116:117], v[112:113]
	v_pk_add_f32 v[116:117], v[124:125], 1.0 op_sel_hi:[1,0]
	v_pk_fma_f32 v[108:109], v[108:109], v[186:187], v[140:141] op_sel_hi:[1,0,1]
	v_rcp_f32_e32 v116, v116
	v_rcp_f32_e32 v117, v117
	v_pk_mul_f32 v[112:113], v[112:113], v[122:123]
	v_lshl_add_u32 v190, s82, 7, v169
	v_cvt_pk_bf16_f32 v122, v112, v113
	v_pk_fma_f32 v[112:113], v[114:115], v[184:185], v[130:131] op_sel_hi:[1,0,1]
	v_ashrrev_i32_e32 v191, 31, v190
	v_pk_mul_f32 v[112:113], v[118:119], v[112:113]
	v_pk_mul_f32 v[118:119], v[108:109], s[28:29] op_sel_hi:[1,0]
	v_pk_mul_f32 v[112:113], v[112:113], v[116:117]
	v_exp_f32_e32 v118, v118
	v_exp_f32_e32 v119, v119
	v_cvt_pk_bf16_f32 v123, v112, v113
	v_mov_b64_e32 v[112:113], s[6:7]
	v_pk_fma_f32 v[104:105], v[104:105], v[186:187], v[136:137] op_sel_hi:[1,0,1]
	v_mad_i64_i32 v[116:117], s[54:55], v180, s10, v[112:113]
	v_lshlrev_b64 v[114:115], 1, v[190:191]
	v_pk_mul_f32 v[104:105], v[108:109], v[104:105]
	v_pk_fma_f32 v[108:109], v[110:111], v[186:187], v[142:143] op_sel_hi:[1,0,1]
	v_lshl_add_u64 v[116:117], v[116:117], 0, v[114:115]
	v_pk_mul_f32 v[110:111], v[108:109], s[28:29] op_sel_hi:[1,0]
	global_store_dwordx4 v[116:117], v[120:123], off nt
	v_pk_add_f32 v[116:117], v[118:119], 1.0 op_sel_hi:[1,0]
	v_exp_f32_e32 v110, v110
	v_exp_f32_e32 v111, v111
	v_rcp_f32_e32 v116, v116
	v_rcp_f32_e32 v117, v117
	v_pk_fma_f32 v[100:101], v[100:101], v[186:187], v[132:133] op_sel_hi:[1,0,1]
	v_pk_add_f32 v[110:111], v[110:111], 1.0 op_sel_hi:[1,0]
	v_pk_fma_f32 v[106:107], v[106:107], v[186:187], v[138:139] op_sel_hi:[1,0,1]
	v_pk_mul_f32 v[104:105], v[104:105], v[116:117]
	v_rcp_f32_e32 v110, v110
	v_rcp_f32_e32 v111, v111
	v_pk_mul_f32 v[116:117], v[100:101], s[28:29] op_sel_hi:[1,0]
	v_pk_fma_f32 v[102:103], v[102:103], v[186:187], v[134:135] op_sel_hi:[1,0,1]
	v_exp_f32_e32 v116, v116
	v_exp_f32_e32 v117, v117
	v_pk_mul_f32 v[106:107], v[108:109], v[106:107]
	v_pk_mul_f32 v[108:109], v[102:103], s[28:29] op_sel_hi:[1,0]
	v_pk_mul_f32 v[106:107], v[106:107], v[110:111]
	v_exp_f32_e32 v108, v108
	v_exp_f32_e32 v109, v109
	v_cvt_pk_bf16_f32 v104, v104, v105
	v_cvt_pk_bf16_f32 v105, v106, v107
	v_pk_add_f32 v[106:107], v[116:117], 1.0 op_sel_hi:[1,0]
	v_pk_fma_f32 v[96:97], v[96:97], v[186:187], v[128:129] op_sel_hi:[1,0,1]
	v_rcp_f32_e32 v106, v106
	v_rcp_f32_e32 v107, v107
	v_pk_mul_f32 v[96:97], v[100:101], v[96:97]
	v_pk_add_f32 v[100:101], v[108:109], 1.0 op_sel_hi:[1,0]
	v_pk_fma_f32 v[92:93], v[92:93], v[182:183], v[140:141] op_sel_hi:[1,0,1]
	v_rcp_f32_e32 v100, v100
	v_rcp_f32_e32 v101, v101
	v_pk_mul_f32 v[96:97], v[96:97], v[106:107]
	v_pk_fma_f32 v[88:89], v[88:89], v[182:183], v[136:137] op_sel_hi:[1,0,1]
	v_cvt_pk_bf16_f32 v106, v96, v97
	v_pk_fma_f32 v[96:97], v[98:99], v[186:187], v[130:131] op_sel_hi:[1,0,1]
	v_pk_mul_f32 v[98:99], v[92:93], s[28:29] op_sel_hi:[1,0]
	v_pk_mul_f32 v[96:97], v[102:103], v[96:97]
	v_exp_f32_e32 v98, v98
	v_exp_f32_e32 v99, v99
	v_pk_mul_f32 v[96:97], v[96:97], v[100:101]
	v_pk_mul_f32 v[88:89], v[92:93], v[88:89]
	v_cvt_pk_bf16_f32 v107, v96, v97
	v_mad_i64_i32 v[96:97], s[54:55], v178, s10, v[112:113]
	v_pk_fma_f32 v[92:93], v[94:95], v[182:183], v[142:143] op_sel_hi:[1,0,1]
	v_lshl_add_u64 v[96:97], v[96:97], 0, v[114:115]
	v_pk_mul_f32 v[94:95], v[92:93], s[28:29] op_sel_hi:[1,0]
	global_store_dwordx4 v[96:97], v[104:107], off nt
	v_pk_add_f32 v[96:97], v[98:99], 1.0 op_sel_hi:[1,0]
	v_exp_f32_e32 v94, v94
	v_exp_f32_e32 v95, v95
	v_rcp_f32_e32 v96, v96
	v_rcp_f32_e32 v97, v97
	v_pk_fma_f32 v[84:85], v[84:85], v[182:183], v[132:133] op_sel_hi:[1,0,1]
	v_pk_add_f32 v[94:95], v[94:95], 1.0 op_sel_hi:[1,0]
	v_pk_fma_f32 v[90:91], v[90:91], v[182:183], v[138:139] op_sel_hi:[1,0,1]
	v_pk_mul_f32 v[88:89], v[88:89], v[96:97]
	v_rcp_f32_e32 v94, v94
	v_rcp_f32_e32 v95, v95
	v_pk_mul_f32 v[96:97], v[84:85], s[28:29] op_sel_hi:[1,0]
	v_pk_fma_f32 v[86:87], v[86:87], v[182:183], v[134:135] op_sel_hi:[1,0,1]
	v_exp_f32_e32 v96, v96
; __device__ __forceinline__ unsigned cvt_pk_bf16(float lo, float hi) { unsigned r; asm volatile("v_cvt_pk_bf16_f32 %0, %1, %2" : "=v"(r) : "v"(lo), "v"(hi)); return r; }
;     __device__ __forceinline__ void operator()(const f32x4 (&acc)[2][2][4][2], const Unit& u, int wr, int wc, int fr, int fq) const {
;     ...
; #pragma unroll
;         for (int ai = 0; ai < 2; ++ai)
; #pragma unroll
;             for (int m = 0; m < 4; ++m) { const size_t row = (size_t)(u.pm * BM + ai * HALF + wr * 64 + m * 16 + fr); const float rs = rsv[ai][m];
;                 u32x4 w;
; #pragma unroll
;                 for (int n = 0; n < 2; ++n)
; #pragma unroll
;                     for (int h = 0; h < 2; ++h) {
;                         const f32x2_t ag = {acc[ai][0][m][n][2 * h], acc[ai][0][m][n][2 * h + 1]}, au = {acc[ai][1][m][n][2 * h], acc[ai][1][m][n][2 * h + 1]};
;                         const f32x4 bgv = n ? bg1 : bg0, buv = n ? bu1 : bu0;
;                         const f32x2_t bg = {bgv[2 * h], bgv[2 * h + 1]}, bu = {buv[2 * h], buv[2 * h + 1]};
;                         const f32x2_t g = ag * rs + bg, up = au * rs + bu, ea = g * (-1.4426950408889634f);
;                         f32x2_t ex; ex.x = __builtin_amdgcn_exp2f(ea.x); ex.y = __builtin_amdgcn_exp2f(ea.y);
;                         const f32x2_t d = ex + 1.0f; f32x2_t rc; rc.x = __builtin_amdgcn_rcpf(d.x); rc.y = __builtin_amdgcn_rcpf(d.y);
;                         const f32x2_t o = (g * up) * rc;
;                         w[n * 2 + h] = cvt_pk_bf16(o.x, o.y); }
;                 __builtin_nontemporal_store(w, (u32x4*)(act + row * XDFF + col0)); }
	v_exp_f32_e32 v97, v97
	v_pk_mul_f32 v[90:91], v[92:93], v[90:91]
	v_pk_mul_f32 v[92:93], v[86:87], s[28:29] op_sel_hi:[1,0]
	v_pk_mul_f32 v[90:91], v[90:91], v[94:95]
	v_exp_f32_e32 v92, v92
	v_exp_f32_e32 v93, v93
	v_cvt_pk_bf16_f32 v88, v88, v89
	v_cvt_pk_bf16_f32 v89, v90, v91
	v_pk_add_f32 v[90:91], v[96:97], 1.0 op_sel_hi:[1,0]
	v_pk_fma_f32 v[80:81], v[80:81], v[182:183], v[128:129] op_sel_hi:[1,0,1]
	v_rcp_f32_e32 v90, v90
	v_rcp_f32_e32 v91, v91
	v_pk_mul_f32 v[80:81], v[84:85], v[80:81]
	v_pk_add_f32 v[84:85], v[92:93], 1.0 op_sel_hi:[1,0]
	v_pk_fma_f32 v[76:77], v[76:77], v[176:177], v[140:141] op_sel_hi:[1,0,1]
	v_rcp_f32_e32 v84, v84
	v_rcp_f32_e32 v85, v85
	v_pk_mul_f32 v[80:81], v[80:81], v[90:91]
	v_pk_fma_f32 v[72:73], v[72:73], v[176:177], v[136:137] op_sel_hi:[1,0,1]
	v_cvt_pk_bf16_f32 v90, v80, v81
	v_pk_fma_f32 v[80:81], v[82:83], v[182:183], v[130:131] op_sel_hi:[1,0,1]
	v_pk_mul_f32 v[82:83], v[76:77], s[28:29] op_sel_hi:[1,0]
	v_pk_mul_f32 v[80:81], v[86:87], v[80:81]
	v_exp_f32_e32 v82, v82
	v_exp_f32_e32 v83, v83
	v_pk_mul_f32 v[80:81], v[80:81], v[84:85]
	v_pk_mul_f32 v[72:73], v[76:77], v[72:73]
	v_cvt_pk_bf16_f32 v91, v80, v81
	v_mad_i64_i32 v[80:81], s[54:55], v174, s10, v[112:113]
	v_pk_fma_f32 v[76:77], v[78:79], v[176:177], v[142:143] op_sel_hi:[1,0,1]
	v_lshl_add_u64 v[80:81], v[80:81], 0, v[114:115]
	v_pk_mul_f32 v[78:79], v[76:77], s[28:29] op_sel_hi:[1,0]
	global_store_dwordx4 v[80:81], v[88:91], off nt
	v_pk_add_f32 v[80:81], v[82:83], 1.0 op_sel_hi:[1,0]
	v_exp_f32_e32 v78, v78
	v_exp_f32_e32 v79, v79
	v_rcp_f32_e32 v80, v80
	v_rcp_f32_e32 v81, v81
	v_pk_fma_f32 v[68:69], v[68:69], v[176:177], v[132:133] op_sel_hi:[1,0,1]
	v_pk_add_f32 v[78:79], v[78:79], 1.0 op_sel_hi:[1,0]
	v_pk_fma_f32 v[74:75], v[74:75], v[176:177], v[138:139] op_sel_hi:[1,0,1]
	v_pk_mul_f32 v[72:73], v[72:73], v[80:81]
	v_rcp_f32_e32 v78, v78
	v_rcp_f32_e32 v79, v79
	v_pk_mul_f32 v[80:81], v[68:69], s[28:29] op_sel_hi:[1,0]
	v_pk_fma_f32 v[70:71], v[70:71], v[176:177], v[134:135] op_sel_hi:[1,0,1]
	v_exp_f32_e32 v80, v80
	v_exp_f32_e32 v81, v81
	v_pk_mul_f32 v[74:75], v[76:77], v[74:75]
	v_pk_mul_f32 v[76:77], v[70:71], s[28:29] op_sel_hi:[1,0]
	v_pk_mul_f32 v[74:75], v[74:75], v[78:79]
	v_exp_f32_e32 v76, v76
	v_exp_f32_e32 v77, v77
	v_cvt_pk_bf16_f32 v72, v72, v73
	v_cvt_pk_bf16_f32 v73, v74, v75
	v_pk_add_f32 v[74:75], v[80:81], 1.0 op_sel_hi:[1,0]
	v_pk_fma_f32 v[64:65], v[64:65], v[176:177], v[128:129] op_sel_hi:[1,0,1]
	v_rcp_f32_e32 v74, v74
	v_rcp_f32_e32 v75, v75
	v_pk_mul_f32 v[64:65], v[68:69], v[64:65]
	v_pk_add_f32 v[68:69], v[76:77], 1.0 op_sel_hi:[1,0]
	v_pk_fma_f32 v[60:61], v[60:61], v[172:173], v[140:141] op_sel_hi:[1,0,1]
	v_rcp_f32_e32 v68, v68
	v_rcp_f32_e32 v69, v69
	v_pk_mul_f32 v[64:65], v[64:65], v[74:75]
	v_pk_fma_f32 v[56:57], v[56:57], v[172:173], v[136:137] op_sel_hi:[1,0,1]
	v_cvt_pk_bf16_f32 v74, v64, v65
	v_pk_fma_f32 v[64:65], v[66:67], v[176:177], v[130:131] op_sel_hi:[1,0,1]
	v_pk_mul_f32 v[66:67], v[60:61], s[28:29] op_sel_hi:[1,0]
	v_pk_mul_f32 v[64:65], v[70:71], v[64:65]
	v_exp_f32_e32 v66, v66
	v_exp_f32_e32 v67, v67
	v_pk_mul_f32 v[64:65], v[64:65], v[68:69]
	v_pk_mul_f32 v[56:57], v[60:61], v[56:57]
	v_cvt_pk_bf16_f32 v75, v64, v65
	v_mad_i64_i32 v[64:65], s[54:55], v170, s10, v[112:113]
	v_pk_fma_f32 v[60:61], v[62:63], v[172:173], v[142:143] op_sel_hi:[1,0,1]
	v_lshl_add_u64 v[64:65], v[64:65], 0, v[114:115]
	v_pk_mul_f32 v[62:63], v[60:61], s[28:29] op_sel_hi:[1,0]
	global_store_dwordx4 v[64:65], v[72:75], off nt
	v_pk_add_f32 v[64:65], v[66:67], 1.0 op_sel_hi:[1,0]
	v_exp_f32_e32 v62, v62
	v_exp_f32_e32 v63, v63
	v_rcp_f32_e32 v64, v64
	v_rcp_f32_e32 v65, v65
	v_pk_fma_f32 v[52:53], v[52:53], v[172:173], v[132:133] op_sel_hi:[1,0,1]
	v_pk_add_f32 v[62:63], v[62:63], 1.0 op_sel_hi:[1,0]
	v_pk_fma_f32 v[58:59], v[58:59], v[172:173], v[138:139] op_sel_hi:[1,0,1]
	v_pk_mul_f32 v[56:57], v[56:57], v[64:65]
	v_rcp_f32_e32 v62, v62
	v_rcp_f32_e32 v63, v63
	v_pk_mul_f32 v[64:65], v[52:53], s[28:29] op_sel_hi:[1,0]
	v_pk_fma_f32 v[54:55], v[54:55], v[172:173], v[134:135] op_sel_hi:[1,0,1]
	v_exp_f32_e32 v64, v64
	v_exp_f32_e32 v65, v65
	v_pk_mul_f32 v[58:59], v[60:61], v[58:59]
	v_pk_mul_f32 v[60:61], v[54:55], s[28:29] op_sel_hi:[1,0]
	v_pk_mul_f32 v[58:59], v[58:59], v[62:63]
	v_exp_f32_e32 v60, v60
	v_exp_f32_e32 v61, v61
	v_cvt_pk_bf16_f32 v56, v56, v57
	v_cvt_pk_bf16_f32 v57, v58, v59
	v_pk_add_f32 v[58:59], v[64:65], 1.0 op_sel_hi:[1,0]
	v_pk_fma_f32 v[48:49], v[48:49], v[172:173], v[128:129] op_sel_hi:[1,0,1]
	v_rcp_f32_e32 v58, v58
	v_rcp_f32_e32 v59, v59
	v_pk_mul_f32 v[48:49], v[52:53], v[48:49]
	v_pk_add_f32 v[52:53], v[60:61], 1.0 op_sel_hi:[1,0]
	v_pk_fma_f32 v[44:45], v[44:45], v[168:169], v[140:141] op_sel_hi:[1,0,1]
	v_rcp_f32_e32 v52, v52
	v_rcp_f32_e32 v53, v53
	v_pk_mul_f32 v[48:49], v[48:49], v[58:59]
	v_pk_fma_f32 v[40:41], v[40:41], v[168:169], v[136:137] op_sel_hi:[1,0,1]
	v_cvt_pk_bf16_f32 v58, v48, v49
	v_pk_fma_f32 v[48:49], v[50:51], v[172:173], v[130:131] op_sel_hi:[1,0,1]
	v_pk_mul_f32 v[50:51], v[44:45], s[28:29] op_sel_hi:[1,0]
	v_pk_mul_f32 v[48:49], v[54:55], v[48:49]
	v_exp_f32_e32 v50, v50
	v_exp_f32_e32 v51, v51
	v_pk_mul_f32 v[48:49], v[48:49], v[52:53]
	v_pk_mul_f32 v[40:41], v[44:45], v[40:41]
	v_cvt_pk_bf16_f32 v59, v48, v49
	v_mad_i64_i32 v[48:49], s[54:55], v166, s10, v[112:113]
	v_pk_fma_f32 v[44:45], v[46:47], v[168:169], v[142:143] op_sel_hi:[1,0,1]
	v_lshl_add_u64 v[48:49], v[48:49], 0, v[114:115]
	v_pk_mul_f32 v[46:47], v[44:45], s[28:29] op_sel_hi:[1,0]
	global_store_dwordx4 v[48:49], v[56:59], off nt
	v_pk_add_f32 v[48:49], v[50:51], 1.0 op_sel_hi:[1,0]
; __device__ __forceinline__ unsigned cvt_pk_bf16(float lo, float hi) { unsigned r; asm volatile("v_cvt_pk_bf16_f32 %0, %1, %2" : "=v"(r) : "v"(lo), "v"(hi)); return r; }
; #define PG8_BAR __builtin_amdgcn_s_barrier()
;     __device__ __forceinline__ void operator()(const f32x4 (&acc)[2][2][4][2], const Unit& u, int wr, int wc, int fr, int fq) const {
;     ...
; #pragma unroll
;         for (int ai = 0; ai < 2; ++ai)
; #pragma unroll
;             for (int m = 0; m < 4; ++m) { const size_t row = (size_t)(u.pm * BM + ai * HALF + wr * 64 + m * 16 + fr); const float rs = rsv[ai][m];
;                 u32x4 w;
; #pragma unroll
;                 for (int n = 0; n < 2; ++n)
; #pragma unroll
;                     for (int h = 0; h < 2; ++h) {
;                         const f32x2_t ag = {acc[ai][0][m][n][2 * h], acc[ai][0][m][n][2 * h + 1]}, au = {acc[ai][1][m][n][2 * h], acc[ai][1][m][n][2 * h + 1]};
;                         const f32x4 bgv = n ? bg1 : bg0, buv = n ? bu1 : bu0;
;                         const f32x2_t bg = {bgv[2 * h], bgv[2 * h + 1]}, bu = {buv[2 * h], buv[2 * h + 1]};
;                         const f32x2_t g = ag * rs + bg, up = au * rs + bu, ea = g * (-1.4426950408889634f);
;                         f32x2_t ex; ex.x = __builtin_amdgcn_exp2f(ea.x); ex.y = __builtin_amdgcn_exp2f(ea.y);
;                         const f32x2_t d = ex + 1.0f; f32x2_t rc; rc.x = __builtin_amdgcn_rcpf(d.x); rc.y = __builtin_amdgcn_rcpf(d.y);
;                         const f32x2_t o = (g * up) * rc;
;                         w[n * 2 + h] = cvt_pk_bf16(o.x, o.y); }
;                 __builtin_nontemporal_store(w, (u32x4*)(act + row * XDFF + col0)); }
; template <class Epi, class Sched, bool ALIGN_EPI = false, bool SP2 = false>
; __device__ __forceinline__ void gemm_phase(PG8_LAS unsigned char* lds, const Gemm g, const Sched& S, const Epi& E, const int wave_s) {
;     ...
;         cur = nxt; cA = nA; cB = nB; ++ui;
;         if constexpr (ALIGN_EPI) { if (wr == 1) PG8_BAR; }
;     }
	v_exp_f32_e32 v46, v46
	v_exp_f32_e32 v47, v47
	v_rcp_f32_e32 v48, v48
	v_rcp_f32_e32 v49, v49
	v_pk_fma_f32 v[36:37], v[36:37], v[168:169], v[132:133] op_sel_hi:[1,0,1]
	v_pk_add_f32 v[46:47], v[46:47], 1.0 op_sel_hi:[1,0]
	v_pk_fma_f32 v[42:43], v[42:43], v[168:169], v[138:139] op_sel_hi:[1,0,1]
	v_pk_mul_f32 v[40:41], v[40:41], v[48:49]
	v_rcp_f32_e32 v46, v46
	v_rcp_f32_e32 v47, v47
	v_pk_mul_f32 v[48:49], v[36:37], s[28:29] op_sel_hi:[1,0]
	v_pk_fma_f32 v[38:39], v[38:39], v[168:169], v[134:135] op_sel_hi:[1,0,1]
	v_exp_f32_e32 v48, v48
	v_exp_f32_e32 v49, v49
	v_pk_mul_f32 v[42:43], v[44:45], v[42:43]
	v_pk_mul_f32 v[44:45], v[38:39], s[28:29] op_sel_hi:[1,0]
	v_pk_mul_f32 v[42:43], v[42:43], v[46:47]
	v_exp_f32_e32 v44, v44
	v_exp_f32_e32 v45, v45
	v_fmamk_f32 v157, v157, 0x30800000, v220
	v_cvt_pk_bf16_f32 v40, v40, v41
	v_cvt_pk_bf16_f32 v41, v42, v43
	v_pk_add_f32 v[42:43], v[48:49], 1.0 op_sel_hi:[1,0]
	v_rsq_f32_e32 v164, v157
	v_rcp_f32_e32 v42, v42
	v_rcp_f32_e32 v43, v43
	v_pk_fma_f32 v[32:33], v[32:33], v[168:169], v[128:129] op_sel_hi:[1,0,1]
	v_pk_fma_f32 v[28:29], v[28:29], v[164:165], v[140:141] op_sel_hi:[1,0,1]
	v_pk_mul_f32 v[32:33], v[36:37], v[32:33]
	v_pk_add_f32 v[36:37], v[44:45], 1.0 op_sel_hi:[1,0]
	v_pk_mul_f32 v[32:33], v[32:33], v[42:43]
	v_rcp_f32_e32 v36, v36
	v_rcp_f32_e32 v37, v37
	v_cvt_pk_bf16_f32 v42, v32, v33
	v_pk_fma_f32 v[32:33], v[34:35], v[168:169], v[130:131] op_sel_hi:[1,0,1]
	v_pk_mul_f32 v[34:35], v[28:29], s[28:29] op_sel_hi:[1,0]
	v_pk_mul_f32 v[32:33], v[38:39], v[32:33]
	v_exp_f32_e32 v34, v34
	v_exp_f32_e32 v35, v35
	v_pk_mul_f32 v[32:33], v[32:33], v[36:37]
	v_pk_fma_f32 v[24:25], v[24:25], v[164:165], v[136:137] op_sel_hi:[1,0,1]
	v_cvt_pk_bf16_f32 v43, v32, v33
	v_mad_i64_i32 v[32:33], s[54:55], v162, s10, v[112:113]
	v_pk_mul_f32 v[24:25], v[28:29], v[24:25]
	v_pk_fma_f32 v[28:29], v[30:31], v[164:165], v[142:143] op_sel_hi:[1,0,1]
	v_lshl_add_u64 v[32:33], v[32:33], 0, v[114:115]
	v_pk_mul_f32 v[30:31], v[28:29], s[28:29] op_sel_hi:[1,0]
	global_store_dwordx4 v[32:33], v[40:43], off nt
	v_pk_add_f32 v[32:33], v[34:35], 1.0 op_sel_hi:[1,0]
	v_exp_f32_e32 v30, v30
	v_exp_f32_e32 v31, v31
	v_rcp_f32_e32 v32, v32
	v_rcp_f32_e32 v33, v33
	v_pk_fma_f32 v[20:21], v[20:21], v[164:165], v[132:133] op_sel_hi:[1,0,1]
	v_pk_add_f32 v[30:31], v[30:31], 1.0 op_sel_hi:[1,0]
	v_cvt_f32_u32_e32 v160, v160
	v_pk_mul_f32 v[24:25], v[24:25], v[32:33]
	v_rcp_f32_e32 v30, v30
	v_rcp_f32_e32 v31, v31
	v_pk_mul_f32 v[32:33], v[20:21], s[28:29] op_sel_hi:[1,0]
	v_pk_fma_f32 v[26:27], v[26:27], v[164:165], v[138:139] op_sel_hi:[1,0,1]
	v_exp_f32_e32 v32, v32
	v_exp_f32_e32 v33, v33
	v_pk_fma_f32 v[22:23], v[22:23], v[164:165], v[134:135] op_sel_hi:[1,0,1]
	v_sub_u32_e32 v157, 32, v159
	v_pk_mul_f32 v[26:27], v[28:29], v[26:27]
	v_pk_mul_f32 v[28:29], v[22:23], s[28:29] op_sel_hi:[1,0]
	v_ldexp_f32 v157, v160, v157
	v_pk_mul_f32 v[26:27], v[26:27], v[30:31]
	v_exp_f32_e32 v28, v28
	v_exp_f32_e32 v29, v29
	v_fmamk_f32 v157, v157, 0x30800000, v220
	v_cvt_pk_bf16_f32 v24, v24, v25
	v_cvt_pk_bf16_f32 v25, v26, v27
	v_pk_add_f32 v[26:27], v[32:33], 1.0 op_sel_hi:[1,0]
	v_rsq_f32_e32 v160, v157
	v_rcp_f32_e32 v26, v26
	v_rcp_f32_e32 v27, v27
	v_pk_fma_f32 v[16:17], v[16:17], v[164:165], v[128:129] op_sel_hi:[1,0,1]
	v_pk_fma_f32 v[12:13], v[12:13], v[160:161], v[140:141] op_sel_hi:[1,0,1]
	v_pk_mul_f32 v[16:17], v[20:21], v[16:17]
	v_pk_add_f32 v[20:21], v[28:29], 1.0 op_sel_hi:[1,0]
	v_pk_mul_f32 v[16:17], v[16:17], v[26:27]
	v_rcp_f32_e32 v20, v20
	v_rcp_f32_e32 v21, v21
	v_cvt_pk_bf16_f32 v26, v16, v17
	v_pk_fma_f32 v[16:17], v[18:19], v[164:165], v[130:131] op_sel_hi:[1,0,1]
	v_pk_mul_f32 v[18:19], v[12:13], s[28:29] op_sel_hi:[1,0]
	v_pk_mul_f32 v[16:17], v[22:23], v[16:17]
	v_exp_f32_e32 v18, v18
	v_exp_f32_e32 v19, v19
	v_pk_mul_f32 v[16:17], v[16:17], v[20:21]
	v_pk_fma_f32 v[8:9], v[8:9], v[160:161], v[136:137] op_sel_hi:[1,0,1]
	v_cvt_pk_bf16_f32 v27, v16, v17
	v_mad_i64_i32 v[16:17], s[54:55], v158, s10, v[112:113]
	v_pk_mul_f32 v[8:9], v[12:13], v[8:9]
	v_pk_fma_f32 v[12:13], v[14:15], v[160:161], v[142:143] op_sel_hi:[1,0,1]
	v_lshl_add_u64 v[16:17], v[16:17], 0, v[114:115]
	v_pk_mul_f32 v[14:15], v[12:13], s[28:29] op_sel_hi:[1,0]
	global_store_dwordx4 v[16:17], v[24:27], off nt
	v_pk_add_f32 v[16:17], v[18:19], 1.0 op_sel_hi:[1,0]
	v_exp_f32_e32 v14, v14
	v_exp_f32_e32 v15, v15
	v_rcp_f32_e32 v16, v16
	v_rcp_f32_e32 v17, v17
	v_pk_fma_f32 v[4:5], v[4:5], v[160:161], v[132:133] op_sel_hi:[1,0,1]
	v_pk_add_f32 v[14:15], v[14:15], 1.0 op_sel_hi:[1,0]
	v_pk_fma_f32 v[10:11], v[10:11], v[160:161], v[138:139] op_sel_hi:[1,0,1]
	v_pk_mul_f32 v[8:9], v[8:9], v[16:17]
	v_rcp_f32_e32 v14, v14
	v_rcp_f32_e32 v15, v15
	v_pk_mul_f32 v[16:17], v[4:5], s[28:29] op_sel_hi:[1,0]
	v_pk_fma_f32 v[6:7], v[6:7], v[160:161], v[134:135] op_sel_hi:[1,0,1]
	v_exp_f32_e32 v16, v16
	v_exp_f32_e32 v17, v17
	v_pk_mul_f32 v[10:11], v[12:13], v[10:11]
	v_pk_mul_f32 v[12:13], v[6:7], s[28:29] op_sel_hi:[1,0]
	v_pk_mul_f32 v[10:11], v[10:11], v[14:15]
	v_exp_f32_e32 v12, v12
	v_exp_f32_e32 v13, v13
	v_cvt_pk_bf16_f32 v8, v8, v9
	v_cvt_pk_bf16_f32 v9, v10, v11
	v_pk_add_f32 v[10:11], v[16:17], 1.0 op_sel_hi:[1,0]
	v_pk_fma_f32 v[0:1], v[0:1], v[160:161], v[128:129] op_sel_hi:[1,0,1]
	v_rcp_f32_e32 v10, v10
	v_rcp_f32_e32 v11, v11
	v_pk_mul_f32 v[0:1], v[4:5], v[0:1]
	v_pk_add_f32 v[4:5], v[12:13], 1.0 op_sel_hi:[1,0]
	v_pk_mul_f32 v[0:1], v[0:1], v[10:11]
	v_rcp_f32_e32 v4, v4
	v_rcp_f32_e32 v5, v5
	v_cvt_pk_bf16_f32 v10, v0, v1
	v_pk_fma_f32 v[0:1], v[2:3], v[160:161], v[130:131] op_sel_hi:[1,0,1]
	s_nop 0
	v_pk_mul_f32 v[0:1], v[6:7], v[0:1]
	s_nop 0
	v_pk_mul_f32 v[0:1], v[0:1], v[4:5]
	s_nop 0
	v_cvt_pk_bf16_f32 v11, v0, v1
	v_mad_i64_i32 v[0:1], s[54:55], v156, s10, v[112:113]
	v_lshl_add_u64 v[0:1], v[0:1], 0, v[114:115]
	global_store_dwordx4 v[0:1], v[8:11], off nt
	s_cbranch_vccnz .LBB0_691
	s_andn2_b64 vcc, exec, s[38:39]
	s_cbranch_vccnz .LBB0_690
	s_barrier
	s_branch .LBB0_690
